# table building (gate fragments, parameter table, zeroing) moved from the prologue into the idle tail of the in-proj GEMM last round
# speedup vs baseline: 1.0889x; 1.0889x over previous
; #define LAS __attribute__((address_space(3)))
; __global__ void __launch_bounds__(NT, 2) trunk_fwd(Args args) {
;     extern __shared__ __attribute__((aligned(16))) unsigned char lds_raw[];
;     LAS unsigned char* lds = (LAS unsigned char*)lds_raw;
;     cg::grid_group grid = cg::this_grid();
;     const Ptrs& P = args.p;
;     const int tid = threadIdx.x, lane = tid & 63, wave = __builtin_amdgcn_readfirstlane(tid >> 6);
;     const int G = gridDim.x, gw = blockIdx.x * NWAVES + wave, NGW = G * NWAVES, gtid = blockIdx.x * NT + tid, GT = G * NT;
;     const int lo = args.ph_lo, hi = args.ph_hi;
;     ...
;     if (tid < 8) ((volatile LAS unsigned*)(lds + 131072))[tid] = 0u;
;     __syncthreads();
;     XcdBarrier bar = xcd_barrier_post((unsigned*)P.ws, (volatile LAS unsigned*)(lds + 131072));
_Z9trunk_fwd4Args:
	s_load_dwordx8 s[52:59], s[0:1], 0x60
	s_load_dwordx8 s[8:15], s[0:1], 0x40
	s_load_dword s61, s[0:1], 0x88
	s_load_dwordx2 s[64:65], s[0:1], 0x80
	s_add_u32 s20, s0, 0x80
	v_and_b32_e32 v184, 0x3ff, v0
	s_mov_b32 s33, s2
	s_addc_u32 s21, s1, 0
	v_readfirstlane_b32 s6, v184
	v_cmp_gt_u32_e32 vcc, 8, v184
	s_and_saveexec_b64 s[2:3], vcc
	v_lshl_add_u32 v1, v184, 2, 0
	v_add_u32_e32 v1, 0x20000, v1
	v_mov_b32_e32 v2, 0
	ds_write_b32 v1, v2
	s_or_b64 exec, exec, s[2:3]
	s_load_dwordx16 s[36:51], s[0:1], 0x0
	s_waitcnt lgkmcnt(0)
	v_writelane_b32 v250, s44, 0
	v_writelane_b32 v250, s45, 1
	v_writelane_b32 v250, s46, 2
	v_writelane_b32 v250, s47, 3
	v_writelane_b32 v250, s48, 4
	v_writelane_b32 v250, s49, 5
	v_writelane_b32 v250, s50, 6
	v_writelane_b32 v250, s51, 7
	v_writelane_b32 v250, s8, 8
	v_writelane_b32 v250, s9, 9
	s_barrier
	s_getreg_b32 s0, hwreg(HW_REG_XCC_ID, 0, 4)
	s_and_b32 s59, s0, 15
	v_cmp_eq_u32_e64 s[0:1], 0, v184
	s_and_saveexec_b64 s[2:3], s[0:1]
	s_cbranch_execz .LBB0_5
	s_mov_b64 s[4:5], exec
	v_mbcnt_lo_u32_b32 v1, s4, 0
	v_mbcnt_hi_u32_b32 v1, s5, v1
	v_cmp_eq_u32_e32 vcc, 0, v1
	s_and_b64 s[16:17], exec, vcc
	s_mov_b64 exec, s[16:17]
	s_cbranch_execz .LBB0_5
	s_lshl_b32 s7, s59, 8
	s_bcnt1_i32_b64 s4, s[4:5]
	v_mov_b32_e32 v1, s7
	v_mov_b32_e32 v2, s4
	global_atomic_add v1, v2, s[54:55] offset:1024

; __device__ __forceinline__ unsigned pk2(float lo, float hi) { f32x2_t v = {lo, hi}; bf16x2_t b = __builtin_convertvector(v, bf16x2_t); return __builtin_bit_cast(unsigned, b); }
; __device__ __forceinline__ void p0_prologue(const Ptrs& P, LAS unsigned char* lds, int gw, int NGW, int wave, int lane, int gtid, int GT, int part) {
;     ...
;     bf16* WGF = (bf16*)(P.ws + WS_WGF);
;     for (int g = gtid; g < LH * 6 * 6 * 64; g += GT) {
;         const int l = g & 63, s = (g >> 6) % 6, tile = (g / 384) % 6, hd = g / 2304, r = l & 31, hh = l >> 5;
;         const int cc = 32 * (tile % 3) + r, col = tile < 3 ? cc : LB + cc; float v[8];
; #pragma unroll
;         for (int j = 0; j < 8; ++j) { const int ch = 16 * s + 8 * (j >> 2) + 4 * hh + (j & 3);
;             v[j] = 0.0f;
;             if (cc < LB) { if (s < 5) v[j] = -LOG2E * P.lwg[((size_t)hd * LB + ch) * (2 * LB) + col]; else if (j == 0 && hh == 0) v[j] = -LOG2E * P.lbg[hd * 2 * LB + col]; } }
;         v4u o; o.x = pk2(v[0], v[1]); o.y = pk2(v[2], v[3]); o.z = pk2(v[4], v[5]); o.w = pk2(v[6], v[7]);
;         *(v4u*)(WGF + (size_t)g * 8) = o;
;     }
.LBB0_45:
	s_and_b64 vcc, exec, s[16:17]
	s_cbranch_vccnz .Lp0_skip_tables
	s_mov_b32 s95, 0
	v_lshl_add_u32 v10, s33, 9, v184
	s_lshl_b32 s22, s64, 9
.Lp0_tables:
	s_mov_b32 s2, 0x9000
	v_cmp_gt_i32_e32 vcc, s2, v10
	v_ashrrev_i32_e32 v11, 31, v10
	s_and_saveexec_b64 s[24:25], vcc
	s_cbranch_execz .LBB0_70
	v_lshl_add_u64 v[2:3], v[10:11], 4, s[54:55]
	s_mov_b64 s[2:3], 0x1600000
	s_ashr_i32 s23, s22, 31
	v_and_b32_e32 v9, 31, v184
	v_lshl_add_u64 v[12:13], v[2:3], 0, s[2:3]
	s_lshl_b64 s[26:27], s[22:23], 4
	s_mov_b32 s23, 0
	s_mov_b64 s[28:29], 0
	s_mov_b32 s69, 0x2aaaaaab
	s_mov_b32 s70, 0x38e38e39
	s_movk_i32 s71, 0x50
	s_movk_i32 s72, 0x4f
	s_movk_i32 s73, 0x280
	s_movk_i32 s74, 0xa0
	s_mov_b32 s75, 0x8fff
	v_mov_b32_e32 v16, v10
	s_branch .LBB0_48

; __device__ __forceinline__ unsigned pk2(float lo, float hi) { f32x2_t v = {lo, hi}; bf16x2_t b = __builtin_convertvector(v, bf16x2_t); return __builtin_bit_cast(unsigned, b); }
; __device__ __forceinline__ void p0_prologue(const Ptrs& P, LAS unsigned char* lds, int gw, int NGW, int wave, int lane, int gtid, int GT, int part) {
;     ...
;     float* ssq0 = (float*)(P.ws + WS_SSQ0); float* ssq1 = (float*)(P.ws + WS_SSQ1); float* ssq2 = (float*)(P.ws + WS_SSQ2);
;     for (int g = gtid; g < M; g += GT) { ssq1[g] = 0.0f; ssq2[g] = 0.0f; }
;     { unsigned long long* XS = (unsigned long long*)(P.ws + WS_X); for (int g = gtid; g < M * 4 + 1024; g += GT) XS[g] = 0ull; }
;     { unsigned long long* GR = (unsigned long long*)(P.ws + WS_SUM); for (int g = gtid; g < 64 * NCHUNK * LB; g += GT) GR[g] = 0ull; }
;     bf16* XB = (bf16*)(P.ws + WS_XB);
;     for (int m0 = gw; m0 < M; m0 += 2 * NGW) {
;         f32x4 v[2][4];
; #pragma unroll
;         for (int q = 0; q < 2; ++q) { const int m = m0 + q * NGW; if (m < M) { const f32x4* xr = (const f32x4*)(P.x + (size_t)m * D) + lane;
; #pragma unroll
;             for (int j = 0; j < 4; ++j) v[q][j] = __builtin_nontemporal_load(xr + 64 * j); } }
; #pragma unroll
;         for (int q = 0; q < 2; ++q) { const int m = m0 + q * NGW; if (m < M) { unsigned long long* o8 = (unsigned long long*)(XB + (size_t)m * D) + lane; float s = 0.f;
; #pragma unroll
;             for (int j = 0; j < 4; ++j) { s += (v[q][j].x * v[q][j].x + v[q][j].y * v[q][j].y) + (v[q][j].z * v[q][j].z + v[q][j].w * v[q][j].w);
;                 o8[64 * j] = (unsigned long long)pk2(v[q][j].x, v[q][j].y) | ((unsigned long long)pk2(v[q][j].z, v[q][j].w) << 32); }
;             s = wave_sum(s); if (lane == 0) ssq0[m] = s; } }
.LBB0_98:
	s_or_b64 exec, exec, s[2:3]
	s_cmp_lg_u32 s95, 0
	s_cbranch_scc1 .Lp1b_tables_ret
.Lp0_skip_tables:
	s_cmpk_gt_i32 s60, 0x3fff
	s_cbranch_scc1 .LBB0_109
	v_lshlrev_b32_e32 v34, 3, v232
	v_mov_b32_e32 v35, 0
	v_lshl_add_u64 v[2:3], s[54:55], 0, v[34:35]
	s_mov_b64 s[2:3], 0x1800000
	v_mbcnt_lo_u32_b32 v1, -1, 0
	v_lshl_add_u64 v[36:37], v[2:3], 0, s[2:3]
	v_mbcnt_hi_u32_b32 v2, -1, v1
	v_and_b32_e32 v1, 64, v2
	v_add_u32_e32 v3, 64, v1
	v_xor_b32_e32 v1, 1, v2
	v_cmp_lt_i32_e32 vcc, v1, v3
	v_xor_b32_e32 v4, 2, v2
	s_add_u32 s24, s54, 0x100000
	v_cndmask_b32_e32 v1, v2, v1, vcc
	v_cmp_lt_i32_e32 vcc, v4, v3
	v_lshlrev_b32_e32 v34, 4, v232
	s_addc_u32 s25, s55, 0
	v_cndmask_b32_e32 v4, v2, v4, vcc
	v_lshlrev_b32_e32 v40, 2, v4
	v_xor_b32_e32 v4, 4, v2
	v_cmp_lt_i32_e32 vcc, v4, v3
	v_cmp_eq_u32_e64 s[2:3], 0, v232
	v_lshlrev_b32_e32 v1, 2, v1
	v_cndmask_b32_e32 v4, v2, v4, vcc
	v_lshlrev_b32_e32 v41, 2, v4
	v_xor_b32_e32 v4, 8, v2
	v_cmp_lt_i32_e32 vcc, v4, v3
	v_lshl_add_u64 v[38:39], s[36:37], 0, v[34:35]
	s_mov_b32 s6, s60
	v_cndmask_b32_e32 v4, v2, v4, vcc
	v_lshlrev_b32_e32 v42, 2, v4
	v_xor_b32_e32 v4, 16, v2
	v_cmp_lt_i32_e32 vcc, v4, v3
	s_nop 1
	v_cndmask_b32_e32 v4, v2, v4, vcc
	v_lshlrev_b32_e32 v43, 2, v4
	v_xor_b32_e32 v4, 32, v2
	v_cmp_lt_i32_e32 vcc, v4, v3
	s_nop 1
	v_cndmask_b32_e32 v2, v2, v4, vcc
	v_lshlrev_b32_e32 v44, 2, v2
	s_branch .LBB0_102

; __global__ void __launch_bounds__(NT, 2) trunk_fwd(Args args) {
;     ...
;         pg8::gemm_phase<pg8::EpiLruIn, pg8::StaticOrder, true, true>(lds, g, S, E);
;         if (split_p0 && blockIdx.x >= 128) { __syncthreads(); p0_prologue(P, lds, (blockIdx.x - 128) * NWAVES + wave, 128 * NWAVES, wave, lane, 0, 1, 2); __syncthreads(); }
.LBB0_235:
	s_barrier
	s_mov_b64 s[96:97], s[4:5]
	s_mov_b32 s98, s22
	s_mov_b32 s99, s24
	v_readlane_b32 s44, v250, 0
	v_readlane_b32 s45, v250, 1
	v_readlane_b32 s46, v250, 2
	v_readlane_b32 s47, v250, 3
	v_readlane_b32 s48, v250, 4
	v_readlane_b32 s49, v250, 5
	v_readlane_b32 s50, v250, 6
	v_readlane_b32 s51, v250, 7
	v_readlane_b32 s8, v250, 8
	v_readlane_b32 s9, v250, 9
	s_add_i32 s100, s33, 0xffffff80
	v_lshl_add_u32 v10, s100, 9, v184
	s_mov_b32 s22, 0x10000
	s_mov_b32 s95, 1
	s_branch .Lp0_tables
.Lp1b_tables_ret:
	s_mov_b64 s[4:5], s[96:97]
	s_mov_b32 s22, s98
	s_mov_b32 s24, s99

; __global__ void __launch_bounds__(NT, 2) trunk_fwd(Args args) {
;     extern __shared__ __attribute__((aligned(16))) unsigned char lds_raw[];
	.amdhsa_kernel _Z9trunk_fwd4Args
		.amdhsa_group_segment_fixed_size 0
		.amdhsa_private_segment_fixed_size 0
		.amdhsa_kernarg_size 384
		.amdhsa_user_sgpr_count 2
		.amdhsa_user_sgpr_dispatch_ptr 0
		.amdhsa_user_sgpr_queue_ptr 0
		.amdhsa_user_sgpr_kernarg_segment_ptr 1
		.amdhsa_user_sgpr_dispatch_id 0
		.amdhsa_user_sgpr_kernarg_preload_length 0
		.amdhsa_user_sgpr_kernarg_preload_offset 0
		.amdhsa_user_sgpr_private_segment_size 0
		.amdhsa_uses_dynamic_stack 0
		.amdhsa_enable_private_segment 0
		.amdhsa_system_sgpr_workgroup_id_x 1
		.amdhsa_system_sgpr_workgroup_id_y 0
		.amdhsa_system_sgpr_workgroup_id_z 0
		.amdhsa_system_sgpr_workgroup_info 0
		.amdhsa_system_vgpr_workitem_id 2
		.amdhsa_next_free_vgpr 252
		.amdhsa_next_free_sgpr 101
		.amdhsa_accum_offset 252
		.amdhsa_reserve_vcc 1
		.amdhsa_float_round_mode_32 0
		.amdhsa_float_round_mode_16_64 0
		.amdhsa_float_denorm_mode_32 3
		.amdhsa_float_denorm_mode_16_64 3
		.amdhsa_dx10_clamp 1
		.amdhsa_ieee_mode 1
		.amdhsa_fp16_overflow 0
		.amdhsa_tg_split 0
		.amdhsa_exception_fp_ieee_invalid_op 0
		.amdhsa_exception_fp_denorm_src 0
		.amdhsa_exception_fp_ieee_div_zero 0
		.amdhsa_exception_fp_ieee_overflow 0
		.amdhsa_exception_fp_ieee_underflow 0
		.amdhsa_exception_fp_ieee_inexact 0
		.amdhsa_exception_int_div_zero 0
	.end_amdhsa_kernel

; __global__ void __launch_bounds__(NT, 2) trunk_fwd(Args args) {
;     extern __shared__ __attribute__((aligned(16))) unsigned char lds_raw[];
amdhsa.kernels:
  - .agpr_count:     0
    .args:
      - .offset:         0
        .size:           128
        .value_kind:     by_value
      - .offset:         128
        .size:           4
        .value_kind:     hidden_block_count_x
      - .offset:         132
        .size:           4
        .value_kind:     hidden_block_count_y
      - .offset:         136
        .size:           4
        .value_kind:     hidden_block_count_z
      - .offset:         140
        .size:           2
        .value_kind:     hidden_group_size_x
      - .offset:         142
        .size:           2
        .value_kind:     hidden_group_size_y
      - .offset:         144
        .size:           2
        .value_kind:     hidden_group_size_z
      - .offset:         146
        .size:           2
        .value_kind:     hidden_remainder_x
      - .offset:         148
        .size:           2
        .value_kind:     hidden_remainder_y
      - .offset:         150
        .size:           2
        .value_kind:     hidden_remainder_z
      - .offset:         168
        .size:           8
        .value_kind:     hidden_global_offset_x
      - .offset:         176
        .size:           8
        .value_kind:     hidden_global_offset_y
      - .offset:         184
        .size:           8
        .value_kind:     hidden_global_offset_z
      - .offset:         192
        .size:           2
        .value_kind:     hidden_grid_dims
      - .offset:         216
        .size:           8
        .value_kind:     hidden_multigrid_sync_arg
      - .offset:         248
        .size:           4
        .value_kind:     hidden_dynamic_lds_size
    .group_segment_fixed_size: 0
    .kernarg_segment_align: 8
    .kernarg_segment_size: 384
    .language:       OpenCL C
    .language_version:
      - 2
      - 0
    .max_flat_workgroup_size: 512
    .name:           _Z9trunk_fwd4Args
    .private_segment_fixed_size: 0
    .sgpr_count:     107
    .sgpr_spill_count: 0
    .symbol:         _Z9trunk_fwd4Args.kd
    .uniform_work_group_size: 1
    .uses_dynamic_stack: false
    .vgpr_count:     252
    .vgpr_spill_count: 0
    .wavefront_size: 64
